# S5 unit prologue: first u-chunk load issued before the parameter-load wait
# speedup vs baseline: 1.0128x; 1.0013x over previous
; __device__ __forceinline__ int opaque_tid() { int t = threadIdx.x; asm volatile("" : "+v"(t)); return t; }
; #define BAR_LDS() asm volatile("s_waitcnt lgkmcnt(0)\n\ts_barrier" ::: "memory")
; __device__ __forceinline__ void s5_unit(const Args& A, char* lds, int b, int g) {
;     const int tid = opaque_tid(), lane = tid & 63, wave = __builtin_amdgcn_readfirstlane(tid >> 6); const int fr = lane & 15, fq = lane >> 4, r32 = lane & 31, hi = lane >> 5;
;     const bf16* P1 = (const bf16*)(A.ws + WS_BIG); bf16* YD = (bf16*)A.out;
;     const unsigned char* pg = A.ws + WS_S5P + (size_t)g * S5P_STRIDE; const bf16* BbT = (const bf16*)pg; const bf16* Cm = (const bf16*)(pg + 4096); const float* ari = (const float*)(pg + 8192);
;     const int ttile = wave >> 2, ntile = wave & 3;
;     const bf16x8 bfrag = *(const bf16x8*)(BbT + (ntile * 32 + r32) * 16 + 8 * hi);
;     bf16x8 cfrag[4];
; #pragma unroll
;     for (int ks = 0; ks < 4; ++ks) cfrag[ks] = *(const bf16x8*)(Cm + fr * 128 + ks * 32 + 8 * fq);
;     const float ar = ari[lane], ai = ari[64 + lane]; float sr = 0.f, si = 0.f;
;     const float dskip = A.in[I_ODSKIP][g * 16 + fr];
;     const size_t rb0 = (size_t)b * SEQL; const bf16* pU = P1 + (rb0 + ttile * 32 + r32) * LD1 + C1_U + g * 16 + 8 * hi;
;     bf16x8 un = *(const bf16x8*)pU;
;     BAR_LDS();
.LBB0_1346:
	s_and_b32 s8, s42, 31
	v_mov_b32_e32 v14, v220
	s_lshl_b32 s44, s8, 5
	s_and_b32 s8, s43, 31
	s_ashr_i32 s16, s43, 5
	v_readfirstlane_b32 s20, v14
	s_ashr_i32 s45, s20, 6
	s_mul_i32 s17, s8, 0x2200
	v_and_b32_e32 v48, 15, v14
	s_add_u32 s18, s4, s17
	s_addc_u32 s19, s5, 0
	v_lshlrev_b32_e32 v2, 8, v48
	v_mov_b32_e32 v3, v41
	v_and_b32_e32 v45, 31, v14
	v_lshl_add_u64 v[2:3], s[18:19], 0, v[2:3]
	v_and_b32_e32 v4, 48, v14
	v_mov_b32_e32 v5, v41
	v_and_b32_e32 v15, 63, v14
	s_and_b32 s21, s45, 3
	v_lshlrev_b32_e32 v0, 5, v45
	v_lshl_add_u64 v[2:3], v[2:3], 0, v[4:5]
	v_bfe_u32 v46, v14, 5, 1
	v_lshl_or_b32 v40, s21, 10, v0
	v_lshl_add_u64 v[6:7], v[2:3], 0, s[10:11]
	v_add_co_u32_e32 v2, vcc, s26, v2
	v_lshlrev_b32_e32 v8, 2, v15
	v_mov_b32_e32 v9, v41
	v_lshl_add_u64 v[0:1], s[18:19], 0, v[40:41]
	v_lshlrev_b32_e32 v40, 4, v46
	v_addc_co_u32_e32 v3, vcc, 0, v3, vcc
	v_lshl_add_u64 v[10:11], s[18:19], 0, v[8:9]
	s_ashr_i32 s18, s20, 3
	v_lshl_add_u64 v[0:1], v[0:1], 0, v[40:41]
	v_lshl_add_u64 v[12:13], v[10:11], 0, s[12:13]
	v_add_co_u32_e32 v10, vcc, s27, v10
	s_ashr_i32 s17, s16, 31
	s_and_b32 s46, s18, 0xffffffe0
	v_addc_co_u32_e32 v11, vcc, 0, v11, vcc
	flat_load_dwordx4 v[16:19], v[2:3]
	flat_load_dword v44, v[10:11]
	flat_load_dword v47, v[12:13] offset:256
	flat_load_dwordx4 v[20:23], v[0:1]
	flat_load_dwordx4 v[24:27], v[6:7] offset:64
	flat_load_dwordx4 v[28:31], v[6:7] offset:128
	flat_load_dwordx4 v[32:35], v[6:7] offset:192
	v_lshlrev_b32_e32 v0, 2, v48
	s_lshl_b64 s[22:23], s[16:17], 11
	s_ashr_i32 s16, s46, 31
	v_lshl_or_b32 v0, s8, 6, v0
	v_mov_b32_e32 v1, v41
	s_add_u32 s17, s22, s46
	v_lshl_add_u64 v[0:1], s[34:35], 0, v[0:1]
	v_or_b32_e32 v2, s17, v45
	flat_load_dword v57, v[0:1]
	s_addc_u32 s19, s23, s16
	v_mad_u64_u32 v[0:1], s[16:17], v2, s29, v[42:43]
	v_mad_i32_i24 v1, s19, v56, v1
	s_lshl_b32 s8, s8, 5
	v_lshl_add_u64 v[0:1], v[0:1], 0, s[8:9]
	v_lshl_add_u64 v[0:1], v[0:1], 0, v[40:41]
	v_add_co_u32_e32 v0, vcc, s30, v0
	s_mulk_i32 s19, 0x3800
	s_nop 0
	v_addc_co_u32_e32 v1, vcc, 0, v1, vcc
	flat_load_dwordx4 v[36:39], v[0:1] offset:3072
	v_mad_u64_u32 v[0:1], s[16:17], v2, s29, 0
	s_lshl_b32 s16, s21, 7
	s_add_i32 s47, s16, 0
	s_cmp_lt_u32 s20, 64
	s_cselect_b64 s[16:17], -1, 0
	s_cmp_gt_i32 s45, 3
	v_add_u32_e32 v1, s19, v1
	v_mov_b32_e32 v2, s18
	s_cselect_b64 s[18:19], -1, 0
	s_add_u32 s24, s1, s8
	s_addc_u32 s25, s0, 0
	s_cmp_eq_u32 s21, 0
	s_cselect_b64 s[20:21], -1, 0
	s_lshl_b32 s8, s45, 4
	v_bfi_b32 v58, s28, v2, v14
	s_sub_i32 s8, s8, 64
	v_lshrrev_b32_e32 v2, 2, v14
	v_and_b32_e32 v3, 12, v2
	v_or_b32_e32 v5, s8, v48
	v_or_b32_e32 v62, s8, v3
	v_mul_lo_u32 v5, v5, s36
	s_add_u32 s8, s22, s8
	s_waitcnt lgkmcnt(0)
	s_barrier
	v_lshl_or_b32 v7, v46, 2, s46
	v_lshlrev_b32_e32 v2, 1, v48
	v_add3_u32 v64, s33, v5, v4
	s_addc_u32 s22, s23, 0
	v_or_b32_e32 v4, s8, v3
	v_mov_b32_e32 v3, v41
	v_lshlrev_b32_e32 v6, 2, v45
	v_add_u32_e32 v63, s31, v2
	v_mov_b32_e32 v5, s22
	v_lshl_add_u64 v[48:49], s[24:25], 0, v[2:3]
	v_mul_lo_u32 v2, v7, s37
	v_or3_b32 v0, v0, s44, v40
	v_add_u32_e32 v59, s31, v40
	v_lshl_add_u32 v60, v15, 3, 0
	v_add_u32_e32 v61, s33, v8
	v_add3_u32 v65, s47, v6, v2
	v_lshlrev_b64 v[50:51], 12, v[4:5]
	v_lshl_add_u64 v[52:53], s[6:7], 0, v[0:1]
	s_movk_i32 s44, 0xff80
	s_mov_b32 s8, -2
	v_mov_b32_e32 v54, 0
	v_mov_b32_e32 v55, v41
	s_waitcnt vmcnt(0) lgkmcnt(0)
	v_mov_b32_e32 v45, v44
	v_xor_b32_e32 v46, 0x80000000, v47
	s_mov_b32 s99, s45
	v_mov_b32_e32 v136, v44
	v_mov_b32_e32 v137, v47
	v_mul_f32_e32 v138, v136, v44
	v_mul_f32_e32 v139, v136, v47
	v_fmac_f32_e32 v138, v137, v46
	v_fmac_f32_e32 v139, v137, v44
	v_mul_f32_e32 v140, v138, v44
	v_mul_f32_e32 v141, v138, v47
	v_fmac_f32_e32 v140, v139, v46
	v_fmac_f32_e32 v141, v139, v44
	v_mul_f32_e32 v142, v140, v44
	v_mul_f32_e32 v143, v140, v47
	v_fmac_f32_e32 v142, v141, v46
	v_fmac_f32_e32 v143, v141, v44
	v_mul_f32_e32 v144, v142, v44
	v_mul_f32_e32 v145, v142, v47
	v_fmac_f32_e32 v144, v143, v46
	v_fmac_f32_e32 v145, v143, v44
	v_mul_f32_e32 v146, v144, v44
	v_mul_f32_e32 v147, v144, v47
	v_fmac_f32_e32 v146, v145, v46
	v_fmac_f32_e32 v147, v145, v44
	v_mul_f32_e32 v148, v146, v44
	v_mul_f32_e32 v149, v146, v47
	v_fmac_f32_e32 v148, v147, v46
	v_fmac_f32_e32 v149, v147, v44
	v_mul_f32_e32 v150, v148, v44
	v_mul_f32_e32 v151, v148, v47
	v_fmac_f32_e32 v150, v149, v46
	v_fmac_f32_e32 v151, v149, v44
	v_mul_f32_e32 v152, v150, v44
	v_mul_f32_e32 v153, v150, v47
	v_fmac_f32_e32 v152, v151, v46
	v_fmac_f32_e32 v153, v151, v44
	v_mul_f32_e32 v154, v152, v44
	v_mul_f32_e32 v155, v152, v47
	v_fmac_f32_e32 v154, v153, v46
	v_fmac_f32_e32 v155, v153, v44
	v_mul_f32_e32 v156, v154, v44
	v_mul_f32_e32 v157, v154, v47
	v_fmac_f32_e32 v156, v155, v46
	v_fmac_f32_e32 v157, v155, v44
	v_mul_f32_e32 v158, v156, v44
	v_mul_f32_e32 v159, v156, v47
	v_fmac_f32_e32 v158, v157, v46
	v_fmac_f32_e32 v159, v157, v44
	v_mul_f32_e32 v160, v158, v44
	v_mul_f32_e32 v161, v158, v47
	v_fmac_f32_e32 v160, v159, v46
	v_fmac_f32_e32 v161, v159, v44
	v_mul_f32_e32 v162, v160, v44
	v_mul_f32_e32 v163, v160, v47
	v_fmac_f32_e32 v162, v161, v46
	v_fmac_f32_e32 v163, v161, v44
	v_mul_f32_e32 v164, v162, v44
	v_mul_f32_e32 v165, v162, v47
	v_fmac_f32_e32 v164, v163, v46
	v_fmac_f32_e32 v165, v163, v44
	v_mul_f32_e32 v166, v164, v44
	v_mul_f32_e32 v167, v164, v47
	v_fmac_f32_e32 v166, v165, v46
	v_fmac_f32_e32 v167, v165, v44
	s_lshl_b32 s100, s99, 9
	s_add_i32 s100, s100, 0x1b800
	v_add_u32_e32 v216, s100, v60
	v_add_u32_e32 v217, 0x1b800, v60
	s_branch .LBB0_1348
